# v97: GEMM main loop: the 16 per-cluster s_setprio flips replaced by same-size s_nop (A/B of the template's priority toggling)
# baseline (speedup 1.0000x reference)
.LBB0_394:
	s_add_i32 s13, s8, 2
	s_add_u32 s14, s2, 0x80
	s_addc_u32 s9, s3, 0
	s_add_i32 s38, 0, 0x10000
	s_cmp_eq_u32 s85, s8
	s_cselect_b32 s9, s19, s9
	s_cselect_b32 s8, s18, s14
	v_add_u32_e32 v0, s38, v237
	s_cselect_b32 s15, s21, s11
	s_cselect_b32 s14, s20, s10
	s_add_i32 s39, 0, 0x14000
	ds_read_b128 v[130:133], v0
	ds_read_b128 v[134:137], v0 offset:1024
	ds_read_b128 v[138:141], v0 offset:2048
	ds_read_b128 v[142:145], v0 offset:3072
	v_add_u32_e32 v0, s39, v237
	ds_read_b128 v[146:149], v0
	ds_read_b128 v[150:153], v0 offset:1024
	ds_read_b128 v[154:157], v0 offset:2048
	ds_read_b128 v[158:161], v0 offset:3072
	v_lshl_add_u64 v[214:215], s[2:3], 0, v[182:183]
	s_add_i32 m0, s57, 0xc000
	ds_read_b128 v[162:165], v238
	ds_read_b128 v[186:189], v238 offset:1024
	ds_read_b128 v[190:193], v238 offset:2048
	ds_read_b128 v[194:197], v238 offset:3072
	ds_read_b128 v[198:201], v238 offset:4096
	ds_read_b128 v[202:205], v238 offset:5120
	ds_read_b128 v[206:209], v238 offset:6144
	ds_read_b128 v[210:213], v238 offset:7168
	global_load_lds_dwordx4 v[214:215], off
	v_lshl_add_u64 v[214:215], s[2:3], 0, v[184:185]
	s_add_i32 m0, s57, 0xe000
	s_nop 0
	global_load_lds_dwordx4 v[214:215], off
	s_waitcnt vmcnt(8)
	s_waitcnt lgkmcnt(0)
	s_barrier
	s_nop 0
	s_waitcnt lgkmcnt(0)
	v_mfma_f32_16x16x32_bf16 v[126:129], v[130:133], v[162:165], v[126:129]
	v_mfma_f32_16x16x32_bf16 v[122:125], v[138:141], v[162:165], v[122:125]
	v_mfma_f32_16x16x32_bf16 v[110:113], v[130:133], v[190:193], v[110:113]
	v_mfma_f32_16x16x32_bf16 v[106:109], v[138:141], v[190:193], v[106:109]
	v_mfma_f32_16x16x32_bf16 v[94:97], v[130:133], v[198:201], v[94:97]
	v_mfma_f32_16x16x32_bf16 v[90:93], v[138:141], v[198:201], v[90:93]
	v_mfma_f32_16x16x32_bf16 v[78:81], v[130:133], v[206:209], v[78:81]
	v_mfma_f32_16x16x32_bf16 v[74:77], v[138:141], v[206:209], v[74:77]
	v_mfma_f32_16x16x32_bf16 v[126:129], v[134:137], v[186:189], v[126:129]
	v_mfma_f32_16x16x32_bf16 v[122:125], v[142:145], v[186:189], v[122:125]
	v_mfma_f32_16x16x32_bf16 v[110:113], v[134:137], v[194:197], v[110:113]
	v_mfma_f32_16x16x32_bf16 v[106:109], v[142:145], v[194:197], v[106:109]
	v_mfma_f32_16x16x32_bf16 v[94:97], v[134:137], v[202:205], v[94:97]
	v_mfma_f32_16x16x32_bf16 v[90:93], v[142:145], v[202:205], v[90:93]
	v_mfma_f32_16x16x32_bf16 v[78:81], v[134:137], v[210:213], v[78:81]
	v_mfma_f32_16x16x32_bf16 v[74:77], v[142:145], v[210:213], v[74:77]
	s_nop 0
	s_nop 0
	v_mfma_f32_16x16x32_bf16 v[118:121], v[146:149], v[162:165], v[118:121]
	v_mfma_f32_16x16x32_bf16 v[114:117], v[154:157], v[162:165], v[114:117]
	v_mfma_f32_16x16x32_bf16 v[102:105], v[146:149], v[190:193], v[102:105]
	v_mfma_f32_16x16x32_bf16 v[98:101], v[154:157], v[190:193], v[98:101]
	v_mfma_f32_16x16x32_bf16 v[86:89], v[146:149], v[198:201], v[86:89]
	v_mfma_f32_16x16x32_bf16 v[82:85], v[154:157], v[198:201], v[82:85]
	v_mfma_f32_16x16x32_bf16 v[70:73], v[146:149], v[206:209], v[70:73]
	v_mfma_f32_16x16x32_bf16 v[66:69], v[154:157], v[206:209], v[66:69]
	v_mfma_f32_16x16x32_bf16 v[118:121], v[150:153], v[186:189], v[118:121]
	v_mfma_f32_16x16x32_bf16 v[114:117], v[158:161], v[186:189], v[114:117]
	v_mfma_f32_16x16x32_bf16 v[102:105], v[150:153], v[194:197], v[102:105]
	v_mfma_f32_16x16x32_bf16 v[98:101], v[158:161], v[194:197], v[98:101]
	v_mfma_f32_16x16x32_bf16 v[86:89], v[150:153], v[202:205], v[86:89]
	v_mfma_f32_16x16x32_bf16 v[82:85], v[158:161], v[202:205], v[82:85]
	v_mfma_f32_16x16x32_bf16 v[70:73], v[150:153], v[210:213], v[70:73]
	v_mfma_f32_16x16x32_bf16 v[66:69], v[158:161], v[210:213], v[66:69]
	s_nop 0
	s_barrier
	s_add_i32 s38, s38, s56
	v_lshl_add_u64 v[214:215], s[14:15], 0, v[176:177]
	s_mov_b32 m0, s38
	ds_read_b128 v[162:165], v238 offset:16384
	ds_read_b128 v[186:189], v238 offset:17408
	ds_read_b128 v[190:193], v238 offset:18432
	ds_read_b128 v[194:197], v238 offset:19456
	ds_read_b128 v[198:201], v238 offset:20480
	ds_read_b128 v[202:205], v238 offset:21504
	ds_read_b128 v[206:209], v238 offset:22528
	ds_read_b128 v[210:213], v238 offset:23552
	global_load_lds_dwordx4 v[214:215], off
	s_add_i32 m0, s38, 0x2000
	v_lshl_add_u64 v[216:217], s[14:15], 0, v[172:173]
	s_add_u32 s14, s14, s70
	s_addc_u32 s15, s15, s71
	s_add_i32 s38, s39, s56
	global_load_lds_dwordx4 v[216:217], off
	v_lshl_add_u64 v[218:219], s[14:15], 0, v[176:177]
	s_mov_b32 m0, s38
	v_lshl_add_u64 v[220:221], s[14:15], 0, v[172:173]
	global_load_lds_dwordx4 v[218:219], off
	s_add_i32 m0, s38, 0x2000
	v_lshl_add_u64 v[222:223], s[8:9], 0, v[174:175]
	global_load_lds_dwordx4 v[220:221], off
	s_mov_b32 m0, s57
	v_lshl_add_u64 v[240:241], s[8:9], 0, v[170:171]
	global_load_lds_dwordx4 v[222:223], off
	s_mov_b32 m0, s58
	s_nop 0
	global_load_lds_dwordx4 v[240:241], off
	s_waitcnt vmcnt(8)
	s_waitcnt lgkmcnt(0)
	s_barrier
	s_nop 0
	s_waitcnt lgkmcnt(0)
	v_mfma_f32_16x16x32_bf16 v[62:65], v[130:133], v[162:165], v[62:65]
	v_mfma_f32_16x16x32_bf16 v[58:61], v[138:141], v[162:165], v[58:61]
	v_mfma_f32_16x16x32_bf16 v[46:49], v[130:133], v[190:193], v[46:49]
	v_mfma_f32_16x16x32_bf16 v[42:45], v[138:141], v[190:193], v[42:45]
	v_mfma_f32_16x16x32_bf16 v[30:33], v[130:133], v[198:201], v[30:33]
	v_mfma_f32_16x16x32_bf16 v[26:29], v[138:141], v[198:201], v[26:29]
	v_mfma_f32_16x16x32_bf16 v[14:17], v[130:133], v[206:209], v[14:17]
	v_mfma_f32_16x16x32_bf16 v[10:13], v[138:141], v[206:209], v[10:13]
	v_mfma_f32_16x16x32_bf16 v[62:65], v[134:137], v[186:189], v[62:65]
	v_mfma_f32_16x16x32_bf16 v[58:61], v[142:145], v[186:189], v[58:61]
	v_mfma_f32_16x16x32_bf16 v[46:49], v[134:137], v[194:197], v[46:49]
	v_mfma_f32_16x16x32_bf16 v[42:45], v[142:145], v[194:197], v[42:45]
	v_mfma_f32_16x16x32_bf16 v[30:33], v[134:137], v[202:205], v[30:33]
	v_mfma_f32_16x16x32_bf16 v[26:29], v[142:145], v[202:205], v[26:29]
	v_mfma_f32_16x16x32_bf16 v[14:17], v[134:137], v[210:213], v[14:17]
	v_mfma_f32_16x16x32_bf16 v[10:13], v[142:145], v[210:213], v[10:13]
	s_nop 0
	s_nop 0
	v_mfma_f32_16x16x32_bf16 v[54:57], v[146:149], v[162:165], v[54:57]
	v_mfma_f32_16x16x32_bf16 v[50:53], v[154:157], v[162:165], v[50:53]
	v_mfma_f32_16x16x32_bf16 v[38:41], v[146:149], v[190:193], v[38:41]
	v_mfma_f32_16x16x32_bf16 v[34:37], v[154:157], v[190:193], v[34:37]
	v_mfma_f32_16x16x32_bf16 v[22:25], v[146:149], v[198:201], v[22:25]
	v_mfma_f32_16x16x32_bf16 v[18:21], v[154:157], v[198:201], v[18:21]
	v_mfma_f32_16x16x32_bf16 v[6:9], v[146:149], v[206:209], v[6:9]
	v_mfma_f32_16x16x32_bf16 v[2:5], v[154:157], v[206:209], v[2:5]
	v_mfma_f32_16x16x32_bf16 v[54:57], v[150:153], v[186:189], v[54:57]
	v_mfma_f32_16x16x32_bf16 v[50:53], v[158:161], v[186:189], v[50:53]
	v_mfma_f32_16x16x32_bf16 v[38:41], v[150:153], v[194:197], v[38:41]
	v_mfma_f32_16x16x32_bf16 v[34:37], v[158:161], v[194:197], v[34:37]
	v_mfma_f32_16x16x32_bf16 v[22:25], v[150:153], v[202:205], v[22:25]
	v_mfma_f32_16x16x32_bf16 v[18:21], v[158:161], v[202:205], v[18:21]
	v_mfma_f32_16x16x32_bf16 v[6:9], v[150:153], v[210:213], v[6:9]
	v_mfma_f32_16x16x32_bf16 v[2:5], v[158:161], v[210:213], v[2:5]
	s_nop 0
	s_barrier
	s_add_i32 s14, 0, 0x18000
	v_add_u32_e32 v0, s14, v237
	s_add_i32 s15, 0, 0x1c000
	ds_read_b128 v[130:133], v0
	ds_read_b128 v[134:137], v0 offset:1024
	ds_read_b128 v[138:141], v0 offset:2048
	ds_read_b128 v[142:145], v0 offset:3072
	v_add_u32_e32 v0, s15, v237
	ds_read_b128 v[146:149], v0
	ds_read_b128 v[150:153], v0 offset:1024
	ds_read_b128 v[154:157], v0 offset:2048
	ds_read_b128 v[158:161], v0 offset:3072
	s_add_u32 s8, s8, s50
	s_addc_u32 s9, s9, s51
	s_mov_b32 m0, s59
	v_lshl_add_u64 v[242:243], s[8:9], 0, v[174:175]
	ds_read_b128 v[162:165], v238 offset:32768
	ds_read_b128 v[186:189], v238 offset:33792
	ds_read_b128 v[190:193], v238 offset:34816
	ds_read_b128 v[194:197], v238 offset:35840
	ds_read_b128 v[198:201], v238 offset:36864
	ds_read_b128 v[202:205], v238 offset:37888
	ds_read_b128 v[206:209], v238 offset:38912
	ds_read_b128 v[210:213], v238 offset:39936
	global_load_lds_dwordx4 v[242:243], off
	v_lshl_add_u64 v[242:243], s[8:9], 0, v[170:171]
	s_mov_b32 m0, s60
	s_nop 0
	global_load_lds_dwordx4 v[242:243], off
	s_waitcnt vmcnt(8)
	s_waitcnt lgkmcnt(0)
	s_barrier
	s_nop 0
	s_waitcnt lgkmcnt(0)
	v_mfma_f32_16x16x32_bf16 v[126:129], v[130:133], v[162:165], v[126:129]
	v_mfma_f32_16x16x32_bf16 v[122:125], v[138:141], v[162:165], v[122:125]
	v_mfma_f32_16x16x32_bf16 v[110:113], v[130:133], v[190:193], v[110:113]
	v_mfma_f32_16x16x32_bf16 v[106:109], v[138:141], v[190:193], v[106:109]
	v_mfma_f32_16x16x32_bf16 v[94:97], v[130:133], v[198:201], v[94:97]
	v_mfma_f32_16x16x32_bf16 v[90:93], v[138:141], v[198:201], v[90:93]
	v_mfma_f32_16x16x32_bf16 v[78:81], v[130:133], v[206:209], v[78:81]
	v_mfma_f32_16x16x32_bf16 v[74:77], v[138:141], v[206:209], v[74:77]
	v_mfma_f32_16x16x32_bf16 v[126:129], v[134:137], v[186:189], v[126:129]
	v_mfma_f32_16x16x32_bf16 v[122:125], v[142:145], v[186:189], v[122:125]
	v_mfma_f32_16x16x32_bf16 v[110:113], v[134:137], v[194:197], v[110:113]
	v_mfma_f32_16x16x32_bf16 v[106:109], v[142:145], v[194:197], v[106:109]
	v_mfma_f32_16x16x32_bf16 v[94:97], v[134:137], v[202:205], v[94:97]
	v_mfma_f32_16x16x32_bf16 v[90:93], v[142:145], v[202:205], v[90:93]
	v_mfma_f32_16x16x32_bf16 v[78:81], v[134:137], v[210:213], v[78:81]
	v_mfma_f32_16x16x32_bf16 v[74:77], v[142:145], v[210:213], v[74:77]
	s_nop 0
	s_nop 0
	v_mfma_f32_16x16x32_bf16 v[118:121], v[146:149], v[162:165], v[118:121]
	v_mfma_f32_16x16x32_bf16 v[114:117], v[154:157], v[162:165], v[114:117]
	v_mfma_f32_16x16x32_bf16 v[102:105], v[146:149], v[190:193], v[102:105]
	v_mfma_f32_16x16x32_bf16 v[98:101], v[154:157], v[190:193], v[98:101]
	v_mfma_f32_16x16x32_bf16 v[86:89], v[146:149], v[198:201], v[86:89]
	v_mfma_f32_16x16x32_bf16 v[82:85], v[154:157], v[198:201], v[82:85]
	v_mfma_f32_16x16x32_bf16 v[70:73], v[146:149], v[206:209], v[70:73]
	v_mfma_f32_16x16x32_bf16 v[66:69], v[154:157], v[206:209], v[66:69]
	v_mfma_f32_16x16x32_bf16 v[118:121], v[150:153], v[186:189], v[118:121]
	v_mfma_f32_16x16x32_bf16 v[114:117], v[158:161], v[186:189], v[114:117]
	v_mfma_f32_16x16x32_bf16 v[102:105], v[150:153], v[194:197], v[102:105]
	v_mfma_f32_16x16x32_bf16 v[98:101], v[158:161], v[194:197], v[98:101]
	v_mfma_f32_16x16x32_bf16 v[86:89], v[150:153], v[202:205], v[86:89]
	v_mfma_f32_16x16x32_bf16 v[82:85], v[158:161], v[202:205], v[82:85]
	v_mfma_f32_16x16x32_bf16 v[70:73], v[150:153], v[210:213], v[70:73]
	v_mfma_f32_16x16x32_bf16 v[66:69], v[158:161], v[210:213], v[66:69]
	s_nop 0
	s_barrier
	s_add_i32 s8, s14, s56
	v_lshl_add_u64 v[214:215], v[214:215], 0, s[4:5]
	s_mov_b32 m0, s8
	ds_read_b128 v[162:165], v238 offset:49152
	ds_read_b128 v[186:189], v238 offset:50176
	ds_read_b128 v[190:193], v238 offset:51200
	ds_read_b128 v[194:197], v238 offset:52224
	ds_read_b128 v[198:201], v238 offset:53248
	ds_read_b128 v[202:205], v238 offset:54272
	ds_read_b128 v[206:209], v238 offset:55296
	ds_read_b128 v[210:213], v238 offset:56320
	global_load_lds_dwordx4 v[214:215], off
	v_lshl_add_u64 v[214:215], v[216:217], 0, s[4:5]
	s_add_i32 m0, s8, 0x2000
	s_add_i32 s8, s15, s56
	global_load_lds_dwordx4 v[214:215], off
	v_lshl_add_u64 v[214:215], v[218:219], 0, s[4:5]
	s_mov_b32 m0, s8
	s_nop 0
	global_load_lds_dwordx4 v[214:215], off
	v_lshl_add_u64 v[214:215], v[220:221], 0, s[4:5]
	s_add_i32 m0, s8, 0x2000
	s_nop 0
	global_load_lds_dwordx4 v[214:215], off
	v_lshl_add_u64 v[214:215], v[222:223], 0, s[4:5]
	s_mov_b32 m0, s69
	s_nop 0
	global_load_lds_dwordx4 v[214:215], off
	v_lshl_add_u64 v[214:215], v[240:241], 0, s[4:5]
	s_mov_b32 m0, s84
	s_nop 0
	global_load_lds_dwordx4 v[214:215], off
	s_waitcnt vmcnt(8)
	s_waitcnt lgkmcnt(0)
	s_barrier
	s_nop 0
	s_waitcnt lgkmcnt(0)
	v_mfma_f32_16x16x32_bf16 v[62:65], v[130:133], v[162:165], v[62:65]
	v_mfma_f32_16x16x32_bf16 v[58:61], v[138:141], v[162:165], v[58:61]
	v_mfma_f32_16x16x32_bf16 v[46:49], v[130:133], v[190:193], v[46:49]
	v_mfma_f32_16x16x32_bf16 v[42:45], v[138:141], v[190:193], v[42:45]
	v_mfma_f32_16x16x32_bf16 v[30:33], v[130:133], v[198:201], v[30:33]
	v_mfma_f32_16x16x32_bf16 v[26:29], v[138:141], v[198:201], v[26:29]
	v_mfma_f32_16x16x32_bf16 v[14:17], v[130:133], v[206:209], v[14:17]
	v_mfma_f32_16x16x32_bf16 v[10:13], v[138:141], v[206:209], v[10:13]
	v_mfma_f32_16x16x32_bf16 v[62:65], v[134:137], v[186:189], v[62:65]
	v_mfma_f32_16x16x32_bf16 v[58:61], v[142:145], v[186:189], v[58:61]
	v_mfma_f32_16x16x32_bf16 v[46:49], v[134:137], v[194:197], v[46:49]
	v_mfma_f32_16x16x32_bf16 v[42:45], v[142:145], v[194:197], v[42:45]
	v_mfma_f32_16x16x32_bf16 v[30:33], v[134:137], v[202:205], v[30:33]
	v_mfma_f32_16x16x32_bf16 v[26:29], v[142:145], v[202:205], v[26:29]
	v_mfma_f32_16x16x32_bf16 v[14:17], v[134:137], v[210:213], v[14:17]
	v_mfma_f32_16x16x32_bf16 v[10:13], v[142:145], v[210:213], v[10:13]
	s_nop 0
	s_nop 0
	v_mfma_f32_16x16x32_bf16 v[54:57], v[146:149], v[162:165], v[54:57]
	v_mfma_f32_16x16x32_bf16 v[50:53], v[154:157], v[162:165], v[50:53]
	v_mfma_f32_16x16x32_bf16 v[38:41], v[146:149], v[190:193], v[38:41]
	v_mfma_f32_16x16x32_bf16 v[34:37], v[154:157], v[190:193], v[34:37]
	v_mfma_f32_16x16x32_bf16 v[22:25], v[146:149], v[198:201], v[22:25]
	v_mfma_f32_16x16x32_bf16 v[18:21], v[154:157], v[198:201], v[18:21]
	v_mfma_f32_16x16x32_bf16 v[6:9], v[146:149], v[206:209], v[6:9]
	v_mfma_f32_16x16x32_bf16 v[2:5], v[154:157], v[206:209], v[2:5]
	v_mfma_f32_16x16x32_bf16 v[54:57], v[150:153], v[186:189], v[54:57]
	v_mfma_f32_16x16x32_bf16 v[50:53], v[158:161], v[186:189], v[50:53]
	v_mfma_f32_16x16x32_bf16 v[38:41], v[150:153], v[194:197], v[38:41]
	v_mfma_f32_16x16x32_bf16 v[34:37], v[158:161], v[194:197], v[34:37]
	v_mfma_f32_16x16x32_bf16 v[22:25], v[150:153], v[202:205], v[22:25]
	v_mfma_f32_16x16x32_bf16 v[18:21], v[158:161], v[202:205], v[18:21]
	v_mfma_f32_16x16x32_bf16 v[6:9], v[150:153], v[210:213], v[6:9]
	v_mfma_f32_16x16x32_bf16 v[2:5], v[158:161], v[210:213], v[2:5]
	s_nop 0
	s_barrier
	s_add_u32 s2, s2, 0x100
	s_addc_u32 s3, s3, 0
	s_add_u32 s10, s10, 0x100
	s_addc_u32 s11, s11, 0
	s_cmp_ge_u32 s13, s66
	s_mov_b32 s8, s13
	s_cbranch_scc0 .LBB0_394
	s_and_b64 vcc, exec, s[94:95]
	s_cbranch_vccz .LBB0_397
	s_barrier
